# attention with no setprio at all (A/B of v7)
# speedup vs baseline: 1.0014x; 1.0014x over previous
.LBB0_672:
	s_andn2_b64 vcc, exec, s[2:3]
	s_cbranch_vccnz .LBB0_698
	v_max_f32_e32 v3, v5, v5
	v_mul_u32_u24_e32 v2, 0x90, v2
	v_max_f32_e32 v199, v4, v3
	v_add3_u32 v200, 0, v2, v0
	v_sub_f32_e32 v0, v16, v199
	v_exp_f32_e32 v16, v0
	v_sub_f32_e32 v0, v17, v199
	v_exp_f32_e32 v17, v0
	v_sub_f32_e32 v0, v18, v199
	v_exp_f32_e32 v18, v0
	v_sub_f32_e32 v0, v19, v199
	v_exp_f32_e32 v19, v0
	v_sub_f32_e32 v0, v20, v199
	v_exp_f32_e32 v20, v0
	v_sub_f32_e32 v0, v21, v199
	v_exp_f32_e32 v21, v0
	v_sub_f32_e32 v0, v22, v199
	v_exp_f32_e32 v22, v0
	v_sub_f32_e32 v0, v23, v199
	v_exp_f32_e32 v23, v0
	v_sub_f32_e32 v0, v24, v199
	v_exp_f32_e32 v24, v0
	v_sub_f32_e32 v0, v25, v199
	v_exp_f32_e32 v25, v0
	v_sub_f32_e32 v0, v26, v199
	v_exp_f32_e32 v26, v0
	v_sub_f32_e32 v0, v27, v199
	v_exp_f32_e32 v27, v0
	v_sub_f32_e32 v0, v28, v199
	v_exp_f32_e32 v28, v0
	v_sub_f32_e32 v0, v29, v199
	v_exp_f32_e32 v29, v0
	v_sub_f32_e32 v0, v30, v199
	v_exp_f32_e32 v30, v0
	v_sub_f32_e32 v0, v31, v199
	v_exp_f32_e32 v31, v0
	v_sub_f32_e32 v0, v32, v199
	v_exp_f32_e32 v80, v0
	v_sub_f32_e32 v0, v33, v199
	v_exp_f32_e32 v81, v0
	v_sub_f32_e32 v0, v34, v199
	v_exp_f32_e32 v82, v0
	v_sub_f32_e32 v0, v35, v199
	v_exp_f32_e32 v83, v0
	v_sub_f32_e32 v0, v36, v199
	v_exp_f32_e32 v84, v0
	v_sub_f32_e32 v0, v37, v199
	v_exp_f32_e32 v85, v0
	v_sub_f32_e32 v0, v38, v199
	v_exp_f32_e32 v86, v0
	v_sub_f32_e32 v0, v39, v199
	v_exp_f32_e32 v87, v0
	v_sub_f32_e32 v0, v40, v199
	v_exp_f32_e32 v88, v0
	v_sub_f32_e32 v0, v41, v199
	v_exp_f32_e32 v89, v0
	v_sub_f32_e32 v0, v42, v199
	v_exp_f32_e32 v90, v0
	v_sub_f32_e32 v0, v43, v199
	v_exp_f32_e32 v91, v0
	v_sub_f32_e32 v0, v44, v199
	v_exp_f32_e32 v92, v0
	v_sub_f32_e32 v0, v45, v199
	v_exp_f32_e32 v93, v0
	v_sub_f32_e32 v0, v46, v199
	v_exp_f32_e32 v94, v0
	v_sub_f32_e32 v0, v47, v199
	v_exp_f32_e32 v95, v0
	v_mov_b32_e32 v14, v1
	v_mov_b32_e32 v15, v1
	s_lshl_b32 s64, s4, 2
	v_xor_b32_e32 v48, 0x80000000, v199
	v_mov_b32_e32 v0, v1
	v_mov_b32_e32 v2, v1
	v_mov_b32_e32 v3, v1
	v_mov_b32_e32 v4, v1
	v_mov_b32_e32 v5, v1
	v_mov_b32_e32 v6, v1
	v_mov_b32_e32 v7, v1
	v_mov_b32_e32 v8, v1
	v_mov_b32_e32 v9, v1
	v_mov_b32_e32 v10, v1
	v_mov_b32_e32 v11, v1
	v_mov_b32_e32 v12, v1
	v_mov_b32_e32 v13, v1
	v_mov_b64_e32 v[46:47], v[14:15]
	v_mov_b64_e32 v[78:79], v[14:15]
	s_ashr_i32 s65, s63, 6
	v_mov_b32_e32 v49, v48
	v_mov_b32_e32 v50, v48
	v_mov_b32_e32 v51, v48
	v_mov_b32_e32 v52, v48
	v_mov_b32_e32 v53, v48
	v_mov_b32_e32 v54, v48
	v_mov_b32_e32 v55, v48
	v_mov_b32_e32 v56, v48
	v_mov_b32_e32 v57, v48
	v_mov_b32_e32 v58, v48
	v_mov_b32_e32 v59, v48
	v_mov_b32_e32 v60, v48
	v_mov_b32_e32 v61, v48
	v_mov_b32_e32 v62, v48
	v_mov_b32_e32 v63, v48
	s_or_b32 s66, s64, 3
	s_mov_b32 s67, 0
	v_mov_b32_e32 v201, 0
	s_movk_i32 s68, 0xbf
	v_mov_b64_e32 v[44:45], v[12:13]
	v_mov_b64_e32 v[42:43], v[10:11]
	v_mov_b64_e32 v[40:41], v[8:9]
	v_mov_b64_e32 v[38:39], v[6:7]
	v_mov_b64_e32 v[36:37], v[4:5]
	v_mov_b64_e32 v[34:35], v[2:3]
	v_mov_b64_e32 v[32:33], v[0:1]
	v_mov_b64_e32 v[76:77], v[12:13]
	v_mov_b64_e32 v[74:75], v[10:11]
	v_mov_b64_e32 v[72:73], v[8:9]
	v_mov_b64_e32 v[70:71], v[6:7]
	v_mov_b64_e32 v[68:69], v[4:5]
	v_mov_b64_e32 v[66:67], v[2:3]
	v_mov_b64_e32 v[64:65], v[0:1]
	s_bitcmp1_b32 s63, 7
	s_cbranch_scc0 .Latt_prio_done
